# t10 + CUs<128 start in-proj ~1us late (s_sleep 24): leader/follower de-phasing so followers hit L2 lines fetched by leaders
# speedup vs baseline: 1.0042x; 1.0024x over previous
; #define PG8_STAGE(bufoff, gbase, voff) do { _Pragma("unroll") for (int _i = 0; _i < 2; ++_i) \
;         __builtin_amdgcn_global_load_lds((const unsigned*)((const char*)(gbase) + (voff)[_i]), (LAS unsigned*)(lds + (bufoff) + ldsw + _i * 8192), 16, 0, 0); } while (0)
; template <class Epi, class Sched>
; __device__ __forceinline__ void gemm_phase(LAS unsigned char* lds, const Gemm g, const Sched& S, const Epi& E, const int tid) {
;     ...
;     for (int i = 0; i < 2; ++i) { int R, C; stage_rc(tid * 16 + i * 8192, R, C); const int Rb = Epi::PERM ? ((R & ~31) + perm32(R & 31)) : R;
;         voffA[i] = (unsigned)(R * g.lda + C) * 2u; voffB[i] = (unsigned)(Rb * g.ldb + C) * 2u; }
;     const size_t kstep = (size_t)(BK * 2);
;     const size_t hstepA = (size_t)HALF * g.lda * 2, hstepB = (size_t)HALF * g.ldb * 2;
;     const size_t tstepA = 2 * hstepA, tstepB = 2 * hstepB;
;     const unsigned ldsw = (unsigned)wid * 1024u;
;     const int aoff = lds_byte(wr * 64 + fr, fq * 8), boff = lds_byte(wc * 32 + fr, fq * 8);
;     ...
;     Unit cur, nxt; int ui = 0;
;     if (!S.next(0, cur)) return;
;     f32x4 acc[2][2][4][2];
; #pragma unroll
;     for (int a = 0; a < 2; ++a)
; #pragma unroll
;         for (int b = 0; b < 2; ++b)
; #pragma unroll
;             for (int m = 0; m < 4; ++m)
; #pragma unroll
;                 for (int n = 0; n < 2; ++n) acc[a][b][m][n] = (f32x4){0.f, 0.f, 0.f, 0.f};
;     bf16x8 At[4][2], B0[2][2], B1[2][2];
;     const char* cA = (const char*)g.A + (size_t)cur.pm * tstepA; const char* cB = (const char*)g.Bt + (size_t)cur.pn * tstepB;
;     PG8_STAGE(PG8_SB(0, 0), cB, voffB); PG8_STAGE(PG8_SB(0, 1), cB + hstepB, voffB); PG8_STAGE(PG8_SA(0, 0), cA, voffA); PG8_STAGE(PG8_SA(0, 1), cA + hstepA, voffA);
.LBB0_338:
	s_andn2_b64 vcc, exec, s[0:1]
	s_cbranch_vccnz .LBB0_25
	v_ashrrev_i32_e32 v2, 31, v4
	v_lshrrev_b32_e32 v2, 22, v2
	v_add_u32_e32 v2, v4, v2
	v_and_b32_e32 v2, 0xfffffc00, v2
	v_sub_u32_e32 v2, v4, v2
	v_lshrrev_b32_e32 v3, 4, v2
	v_bitop3_b32 v3, v3, v2, 32 bitop3:0x6c
	v_ashrrev_i32_e32 v2, 31, v2
	v_lshrrev_b32_e32 v1, 26, v1
	v_lshrrev_b32_e32 v2, 26, v2
	v_add_u32_e32 v1, v0, v1
	v_add_u32_e32 v2, v3, v2
	v_ashrrev_i32_e32 v1, 6, v1
	v_ashrrev_i32_e32 v10, 6, v2
	v_lshlrev_b32_e32 v5, 3, v1
	v_mul_i32_i24_e32 v6, 64, v10
	v_and_b32_e32 v5, -16, v5
	v_sub_u32_e32 v3, v3, v6
	v_add_u32_e32 v2, v10, v5
	v_lshlrev_b32_e32 v5, 5, v1
	v_ashrrev_i16_sdwa v3, v226, sext(v3) dst_sel:DWORD dst_unused:UNUSED_PAD src0_sel:DWORD src1_sel:BYTE_0
	v_and_b32_e32 v5, 32, v5
	v_bfe_i32 v11, v3, 0, 16
	v_lshlrev_b32_e32 v3, 1, v2
	v_lshrrev_b32_e32 v6, 2, v2
	v_and_b32_e32 v7, 3, v10
	s_mov_b32 s0, 0xfffe0
	v_and_b32_e32 v3, 24, v3
	v_and_b32_e32 v6, 4, v6
	v_and_or_b32 v7, v2, s0, v7
	v_add_lshl_u32 v5, v5, v11, 1
	v_or3_b32 v3, v7, v6, v3
	v_lshl_add_u32 v144, v2, 12, v5
	v_add_u32_e32 v2, 0x2000, v4
	v_lshl_add_u32 v192, v3, 12, v5
	v_ashrrev_i32_e32 v3, 31, v2
	v_lshrrev_b32_e32 v3, 22, v3
	v_add_u32_e32 v3, v2, v3
	v_ashrrev_i32_e32 v12, 10, v3
	v_mul_i32_i24_e32 v3, 0x400, v12
	v_sub_u32_e32 v2, v2, v3
	v_lshrrev_b32_e32 v3, 4, v2
	v_bitop3_b32 v2, v3, v2, 32 bitop3:0x6c
	v_ashrrev_i32_e32 v4, 31, v2
	v_lshrrev_b32_e32 v4, 26, v4
	v_lshlrev_b32_e32 v3, 3, v12
	v_add_u32_e32 v4, v2, v4
	s_add_u32 s10, s74, s4
	v_and_b32_e32 v3, -16, v3
	v_ashrrev_i32_e32 v13, 6, v4
	s_addc_u32 s11, s75, 0
	s_ashr_i32 s4, s8, 6
	v_add_u32_e32 v3, v13, v3
	v_and_b32_e32 v6, 3, v13
	v_and_or_b32 v6, v3, s0, v6
	s_ashr_i32 s15, s8, 8
	s_lshl_b32 s25, s4, 10
	v_readlane_b32 s0, v251, 56
	v_readlane_b32 s1, v251, 57
	s_mov_b32 s2, s0
	s_add_u32 s27, s10, 0x16000000
	s_mul_i32 s1, s2, 0x4600000
	s_addc_u32 s28, s11, 0
	s_mul_hi_i32 s0, s0, 0x4600000
	s_add_u32 s50, s10, s1
	v_and_b32_e32 v4, 0xc0, v4
	s_addc_u32 s51, s11, s0
	s_ashr_i32 s45, s44, 31
	s_ashr_i32 s47, s46, 31
	v_sub_u32_e32 v2, v2, v4
	s_lshl_b64 s[0:1], s[44:45], 20
	s_lshl_b64 s[2:3], s[46:47], 20
	v_ashrrev_i16_sdwa v2, v226, sext(v2) dst_sel:DWORD dst_unused:UNUSED_PAD src0_sel:DWORD src1_sel:BYTE_0
	s_add_u32 s38, s50, s2
	v_lshlrev_b32_e32 v5, 5, v12
	v_bfe_i32 v14, v2, 0, 16
	v_lshlrev_b32_e32 v2, 1, v3
	v_lshrrev_b32_e32 v4, 2, v3
	s_addc_u32 s39, s51, s3
	s_add_i32 s45, s25, 0
	s_cmp_ge_u32 s68, 0x80
	s_cbranch_scc1 .Lstg_skip
	s_sleep 24
